# grid barrier: waiters poll the monotonic cross-XCD arrival counter directly; last leader no longer bumps a release word
# speedup vs baseline: 1.0327x; 1.0085x over previous
.LBB0_103:
	s_or_b64 exec, exec, s[10:11]
	v_cvt_f32_u32_e32 v4, v2
	s_waitcnt vmcnt(0)
	v_readfirstlane_b32 s8, v3
	v_sub_u32_e32 v3, 0, v2
	v_rcp_iflag_f32_e32 v4, v4
	v_add_u32_e32 v5, s8, v1
	v_mul_f32_e32 v4, 0x4f7ffffe, v4
	v_cvt_u32_f32_e32 v4, v4
	v_mul_lo_u32 v1, v3, v4
	v_mul_hi_u32 v1, v4, v1
	v_add_u32_e32 v1, v4, v1
	v_mul_hi_u32 v1, v5, v1
	v_mul_lo_u32 v3, v1, v2
	v_sub_u32_e32 v3, v5, v3
	v_add_u32_e32 v4, 1, v1
	v_cmp_ge_u32_e32 vcc, v3, v2
	s_nop 1
	v_cndmask_b32_e32 v1, v1, v4, vcc
	v_sub_u32_e32 v4, v3, v2
	v_cndmask_b32_e32 v3, v3, v4, vcc
	v_add_u32_e32 v4, 1, v1
	v_cmp_ge_u32_e32 vcc, v3, v2
	v_add_u32_e32 v3, 1, v5
	s_nop 0
	v_cndmask_b32_e32 v1, v1, v4, vcc
	v_mul_lo_u32 v4, v2, v1
	v_add_u32_e32 v2, v4, v2
	v_cmp_ne_u32_e32 vcc, v3, v2
	s_and_saveexec_b64 s[8:9], vcc
	s_xor_b64 s[8:9], exec, s[8:9]
	s_cbranch_execz .LBB0_117
	s_waitcnt lgkmcnt(0)
	v_mov_b32_e32 v0, 0x21824
	ds_read_b32 v0, v0
	s_waitcnt lgkmcnt(0)
	v_mad_u32_u24 v1, v1, v0, v0
	v_mov_b32_e32 v0, 0x3000
	global_load_dword v0, v0, s[40:41] offset:1024 sc1
	s_add_u32 s14, s40, 0x3400
	s_addc_u32 s15, s41, 0
	s_waitcnt vmcnt(0)
	v_cmp_lt_u32_e32 vcc, v0, v1
	s_and_saveexec_b64 s[10:11], vcc
	s_cbranch_execz .LBB0_116
	s_add_u32 s12, s38, 0x1b000200
	s_addc_u32 s13, s39, 0
	s_mov_b32 s26, 1
	s_mov_b64 s[16:17], 0
	v_mov_b32_e32 v0, 0
	s_branch .LBB0_107

.LBB0_111:
	global_load_dword v2, v0, s[14:15] sc1
	s_add_i32 s26, s26, 1
	s_mov_b64 s[22:23], -1
	s_waitcnt vmcnt(0)
	v_cmp_ge_u32_e32 vcc, v2, v1
	s_orn2_b64 s[20:21], vcc, exec
	s_branch .LBB0_106

.LBB0_120:
	s_or_b64 exec, exec, s[10:11]
	v_cvt_f32_u32_e32 v3, v0
	s_waitcnt vmcnt(0)
	v_readfirstlane_b32 s8, v2
	s_add_u32 s10, s38, 0x1b003400
	s_addc_u32 s11, s39, 0
	v_rcp_iflag_f32_e32 v3, v3
	v_add_u32_e32 v1, s8, v1
	v_add_u32_e32 v4, 1, v1
	s_mov_b64 s[12:13], 0
	v_mul_f32_e32 v2, 0x4f7ffffe, v3
	v_cvt_u32_f32_e32 v2, v2
	v_sub_u32_e32 v3, 0, v0
	v_mul_lo_u32 v3, v3, v2
	v_mul_hi_u32 v3, v2, v3
	v_add_u32_e32 v2, v2, v3
	v_mul_hi_u32 v2, v1, v2
	v_mul_lo_u32 v3, v2, v0
	v_sub_u32_e32 v1, v1, v3
	v_add_u32_e32 v5, 1, v2
	v_cmp_ge_u32_e32 vcc, v1, v0
	v_sub_u32_e32 v3, v1, v0
	s_nop 0
	v_cndmask_b32_e32 v2, v2, v5, vcc
	v_cndmask_b32_e32 v1, v1, v3, vcc
	v_add_u32_e32 v3, 1, v2
	v_cmp_ge_u32_e32 vcc, v1, v0
	s_nop 1
	v_cndmask_b32_e32 v2, v2, v3, vcc
	v_mul_lo_u32 v1, v0, v2
	v_add_u32_e32 v0, v1, v0
	v_cmp_ne_u32_e32 vcc, v4, v0
	v_mov_b32_e32 v2, v0
	v_mov_b64_e32 v[0:1], s[10:11]
	s_and_saveexec_b64 s[8:9], vcc
	s_cbranch_execz .LBB0_132
	v_mov_b32_e32 v0, 0
	global_load_dword v1, v0, s[10:11] sc1
	s_mov_b64 s[16:17], 0
	s_waitcnt vmcnt(0)
	v_cmp_lt_u32_e32 vcc, v1, v2
	s_and_saveexec_b64 s[14:15], vcc
	s_cbranch_execz .LBB0_131
	s_add_u32 s12, s38, 0x1b000200
	s_addc_u32 s13, s39, 0
	s_mov_b32 s26, 1
	s_branch .LBB0_124

.LBB0_128:
	global_load_dword v1, v0, s[10:11] sc1
	s_add_i32 s26, s26, 1
	s_mov_b64 s[20:21], -1
	s_waitcnt vmcnt(0)
	v_cmp_ge_u32_e32 vcc, v1, v2
	s_orn2_b64 s[24:25], vcc, exec
	s_branch .LBB0_123

.LBB0_219:
	s_or_b64 exec, exec, s[14:15]
	v_cvt_f32_u32_e32 v4, v2
	s_waitcnt vmcnt(0)
	v_readfirstlane_b32 s6, v3
	v_sub_u32_e32 v3, 0, v2
	v_rcp_iflag_f32_e32 v4, v4
	v_add_u32_e32 v5, s6, v1
	v_mul_f32_e32 v4, 0x4f7ffffe, v4
	v_cvt_u32_f32_e32 v4, v4
	v_mul_lo_u32 v1, v3, v4
	v_mul_hi_u32 v1, v4, v1
	v_add_u32_e32 v1, v4, v1
	v_mul_hi_u32 v1, v5, v1
	v_mul_lo_u32 v3, v1, v2
	v_sub_u32_e32 v3, v5, v3
	v_add_u32_e32 v4, 1, v1
	v_cmp_ge_u32_e32 vcc, v3, v2
	s_nop 1
	v_cndmask_b32_e32 v1, v1, v4, vcc
	v_sub_u32_e32 v4, v3, v2
	v_cndmask_b32_e32 v3, v3, v4, vcc
	v_add_u32_e32 v4, 1, v1
	v_cmp_ge_u32_e32 vcc, v3, v2
	v_add_u32_e32 v3, 1, v5
	s_nop 0
	v_cndmask_b32_e32 v1, v1, v4, vcc
	v_mul_lo_u32 v4, v2, v1
	v_add_u32_e32 v2, v4, v2
	v_cmp_ne_u32_e32 vcc, v3, v2
	s_and_saveexec_b64 s[6:7], vcc
	s_xor_b64 s[12:13], exec, s[6:7]
	s_cbranch_execz .LBB0_233
	s_waitcnt lgkmcnt(0)
	v_mov_b32_e32 v0, 0x21824
	ds_read_b32 v0, v0
	s_waitcnt lgkmcnt(0)
	v_mad_u32_u24 v1, v1, v0, v0
	v_mov_b32_e32 v0, 0x3000
	global_load_dword v0, v0, s[40:41] offset:1024 sc1
	s_add_u32 s18, s40, 0x3400
	s_addc_u32 s19, s41, 0
	s_waitcnt vmcnt(0)
	v_cmp_lt_u32_e32 vcc, v0, v1
	s_and_saveexec_b64 s[14:15], vcc
	s_cbranch_execz .LBB0_232
	s_add_u32 s16, s38, 0x1b000200
	s_addc_u32 s17, s39, 0
	s_mov_b32 s6, 1
	s_mov_b64 s[20:21], 0
	v_mov_b32_e32 v0, 0
	s_branch .LBB0_223

.LBB0_227:
	global_load_dword v2, v0, s[18:19] sc1
	s_add_i32 s6, s6, 1
	s_mov_b64 s[26:27], -1
	s_waitcnt vmcnt(0)
	v_cmp_ge_u32_e32 vcc, v2, v1
	s_orn2_b64 s[24:25], vcc, exec
	s_branch .LBB0_222

.LBB0_236:
	s_or_b64 exec, exec, s[14:15]
	v_cvt_f32_u32_e32 v3, v0
	s_waitcnt vmcnt(0)
	v_readfirstlane_b32 s6, v2
	s_add_u32 s14, s38, 0x1b003400
	s_addc_u32 s15, s39, 0
	v_rcp_iflag_f32_e32 v3, v3
	v_add_u32_e32 v1, s6, v1
	v_add_u32_e32 v4, 1, v1
	s_mov_b64 s[16:17], 0
	v_mul_f32_e32 v2, 0x4f7ffffe, v3
	v_cvt_u32_f32_e32 v2, v2
	v_sub_u32_e32 v3, 0, v0
	v_mul_lo_u32 v3, v3, v2
	v_mul_hi_u32 v3, v2, v3
	v_add_u32_e32 v2, v2, v3
	v_mul_hi_u32 v2, v1, v2
	v_mul_lo_u32 v3, v2, v0
	v_sub_u32_e32 v1, v1, v3
	v_add_u32_e32 v5, 1, v2
	v_cmp_ge_u32_e32 vcc, v1, v0
	v_sub_u32_e32 v3, v1, v0
	s_nop 0
	v_cndmask_b32_e32 v2, v2, v5, vcc
	v_cndmask_b32_e32 v1, v1, v3, vcc
	v_add_u32_e32 v3, 1, v2
	v_cmp_ge_u32_e32 vcc, v1, v0
	s_nop 1
	v_cndmask_b32_e32 v2, v2, v3, vcc
	v_mul_lo_u32 v1, v0, v2
	v_add_u32_e32 v0, v1, v0
	v_cmp_ne_u32_e32 vcc, v4, v0
	v_mov_b32_e32 v2, v0
	v_mov_b64_e32 v[0:1], s[14:15]
	s_and_saveexec_b64 s[12:13], vcc
	s_cbranch_execz .LBB0_248
	v_mov_b32_e32 v0, 0
	global_load_dword v1, v0, s[14:15] sc1
	s_mov_b64 s[20:21], 0
	s_waitcnt vmcnt(0)
	v_cmp_lt_u32_e32 vcc, v1, v2
	s_and_saveexec_b64 s[18:19], vcc
	s_cbranch_execz .LBB0_247
	s_add_u32 s16, s38, 0x1b000200
	s_addc_u32 s17, s39, 0
	s_mov_b32 s6, 1
	s_branch .LBB0_240

.LBB0_244:
	global_load_dword v1, v0, s[14:15] sc1
	s_add_i32 s6, s6, 1
	s_mov_b64 s[24:25], -1
	s_waitcnt vmcnt(0)
	v_cmp_ge_u32_e32 vcc, v1, v2
	s_orn2_b64 s[30:31], vcc, exec
	s_branch .LBB0_239

.LBB0_284:
	s_or_b64 exec, exec, s[14:15]
	v_cvt_f32_u32_e32 v4, v2
	s_waitcnt vmcnt(0)
	v_readfirstlane_b32 s12, v3
	v_sub_u32_e32 v3, 0, v2
	v_rcp_iflag_f32_e32 v4, v4
	v_add_u32_e32 v5, s12, v1
	v_mul_f32_e32 v4, 0x4f7ffffe, v4
	v_cvt_u32_f32_e32 v4, v4
	v_mul_lo_u32 v1, v3, v4
	v_mul_hi_u32 v1, v4, v1
	v_add_u32_e32 v1, v4, v1
	v_mul_hi_u32 v1, v5, v1
	v_mul_lo_u32 v3, v1, v2
	v_sub_u32_e32 v3, v5, v3
	v_add_u32_e32 v4, 1, v1
	v_cmp_ge_u32_e32 vcc, v3, v2
	s_nop 1
	v_cndmask_b32_e32 v1, v1, v4, vcc
	v_sub_u32_e32 v4, v3, v2
	v_cndmask_b32_e32 v3, v3, v4, vcc
	v_add_u32_e32 v4, 1, v1
	v_cmp_ge_u32_e32 vcc, v3, v2
	v_add_u32_e32 v3, 1, v5
	s_nop 0
	v_cndmask_b32_e32 v1, v1, v4, vcc
	v_mul_lo_u32 v4, v2, v1
	v_add_u32_e32 v2, v4, v2
	v_cmp_ne_u32_e32 vcc, v3, v2
	s_and_saveexec_b64 s[12:13], vcc
	s_xor_b64 s[12:13], exec, s[12:13]
	s_cbranch_execz .LBB0_298
	s_waitcnt lgkmcnt(0)
	v_mov_b32_e32 v0, 0x21824
	ds_read_b32 v0, v0
	s_waitcnt lgkmcnt(0)
	v_mad_u32_u24 v1, v1, v0, v0
	v_mov_b32_e32 v0, 0x3000
	global_load_dword v0, v0, s[40:41] offset:1024 sc1
	s_add_u32 s18, s40, 0x3400
	s_addc_u32 s19, s41, 0
	s_waitcnt vmcnt(0)
	v_cmp_lt_u32_e32 vcc, v0, v1
	s_and_saveexec_b64 s[14:15], vcc
	s_cbranch_execz .LBB0_297
	s_add_u32 s16, s38, 0x1b000200
	s_addc_u32 s17, s39, 0
	s_mov_b32 s34, 1
	s_mov_b64 s[20:21], 0
	v_mov_b32_e32 v0, 0
	s_branch .LBB0_288

.LBB0_292:
	global_load_dword v2, v0, s[18:19] sc1
	s_add_i32 s34, s34, 1
	s_mov_b64 s[26:27], -1
	s_waitcnt vmcnt(0)
	v_cmp_ge_u32_e32 vcc, v2, v1
	s_orn2_b64 s[24:25], vcc, exec
	s_branch .LBB0_287

.LBB0_301:
	s_or_b64 exec, exec, s[14:15]
	v_cvt_f32_u32_e32 v3, v0
	s_waitcnt vmcnt(0)
	v_readfirstlane_b32 s12, v2
	s_add_u32 s14, s38, 0x1b003400
	s_addc_u32 s15, s39, 0
	v_rcp_iflag_f32_e32 v3, v3
	v_add_u32_e32 v1, s12, v1
	v_add_u32_e32 v4, 1, v1
	s_mov_b64 s[16:17], 0
	v_mul_f32_e32 v2, 0x4f7ffffe, v3
	v_cvt_u32_f32_e32 v2, v2
	v_sub_u32_e32 v3, 0, v0
	v_mul_lo_u32 v3, v3, v2
	v_mul_hi_u32 v3, v2, v3
	v_add_u32_e32 v2, v2, v3
	v_mul_hi_u32 v2, v1, v2
	v_mul_lo_u32 v3, v2, v0
	v_sub_u32_e32 v1, v1, v3
	v_add_u32_e32 v5, 1, v2
	v_cmp_ge_u32_e32 vcc, v1, v0
	v_sub_u32_e32 v3, v1, v0
	s_nop 0
	v_cndmask_b32_e32 v2, v2, v5, vcc
	v_cndmask_b32_e32 v1, v1, v3, vcc
	v_add_u32_e32 v3, 1, v2
	v_cmp_ge_u32_e32 vcc, v1, v0
	s_nop 1
	v_cndmask_b32_e32 v2, v2, v3, vcc
	v_mul_lo_u32 v1, v0, v2
	v_add_u32_e32 v0, v1, v0
	v_cmp_ne_u32_e32 vcc, v4, v0
	v_mov_b32_e32 v2, v0
	v_mov_b64_e32 v[0:1], s[14:15]
	s_and_saveexec_b64 s[12:13], vcc
	s_cbranch_execz .LBB0_313
	v_mov_b32_e32 v0, 0
	global_load_dword v1, v0, s[14:15] sc1
	s_mov_b64 s[20:21], 0
	s_waitcnt vmcnt(0)
	v_cmp_lt_u32_e32 vcc, v1, v2
	s_and_saveexec_b64 s[18:19], vcc
	s_cbranch_execz .LBB0_312
	s_add_u32 s16, s38, 0x1b000200
	s_addc_u32 s17, s39, 0
	s_mov_b32 s34, 1
	s_branch .LBB0_305

.LBB0_309:
	global_load_dword v1, v0, s[14:15] sc1
	s_add_i32 s34, s34, 1
	s_mov_b64 s[24:25], -1
	s_waitcnt vmcnt(0)
	v_cmp_ge_u32_e32 vcc, v1, v2
	s_orn2_b64 s[30:31], vcc, exec
	s_branch .LBB0_304

.LBB0_482:
	s_or_b64 exec, exec, s[16:17]
	v_cvt_f32_u32_e32 v3, v0
	s_waitcnt vmcnt(0)
	v_readfirstlane_b32 s6, v2
	s_add_u32 s16, s38, 0x1b003400
	s_addc_u32 s17, s39, 0
	v_rcp_iflag_f32_e32 v3, v3
	v_add_u32_e32 v1, s6, v1
	v_add_u32_e32 v4, 1, v1
	s_mov_b64 s[18:19], 0
	v_mul_f32_e32 v2, 0x4f7ffffe, v3
	v_cvt_u32_f32_e32 v2, v2
	v_sub_u32_e32 v3, 0, v0
	v_mul_lo_u32 v3, v3, v2
	v_mul_hi_u32 v3, v2, v3
	v_add_u32_e32 v2, v2, v3
	v_mul_hi_u32 v2, v1, v2
	v_mul_lo_u32 v3, v2, v0
	v_sub_u32_e32 v1, v1, v3
	v_add_u32_e32 v5, 1, v2
	v_cmp_ge_u32_e32 vcc, v1, v0
	v_sub_u32_e32 v3, v1, v0
	s_nop 0
	v_cndmask_b32_e32 v2, v2, v5, vcc
	v_cndmask_b32_e32 v1, v1, v3, vcc
	v_add_u32_e32 v3, 1, v2
	v_cmp_ge_u32_e32 vcc, v1, v0
	s_nop 1
	v_cndmask_b32_e32 v2, v2, v3, vcc
	v_mul_lo_u32 v1, v0, v2
	v_add_u32_e32 v0, v1, v0
	v_cmp_ne_u32_e32 vcc, v4, v0
	v_mov_b32_e32 v2, v0
	v_mov_b64_e32 v[0:1], s[16:17]
	s_and_saveexec_b64 s[14:15], vcc
	s_cbranch_execz .LBB0_494
	v_mov_b32_e32 v0, 0
	global_load_dword v1, v0, s[16:17] sc1
	s_mov_b64 s[22:23], 0
	s_waitcnt vmcnt(0)
	v_cmp_lt_u32_e32 vcc, v1, v2
	s_and_saveexec_b64 s[20:21], vcc
	s_cbranch_execz .LBB0_493
	s_add_u32 s18, s38, 0x1b000200
	s_addc_u32 s19, s39, 0
	s_mov_b32 s6, 1
	s_branch .LBB0_486

.LBB0_490:
	global_load_dword v1, v0, s[16:17] sc1
	s_add_i32 s6, s6, 1
	s_mov_b64 s[26:27], -1
	s_waitcnt vmcnt(0)
	v_cmp_ge_u32_e32 vcc, v1, v2
	s_orn2_b64 s[34:35], vcc, exec
	s_branch .LBB0_485

.LBB0_993:
	s_or_b64 exec, exec, s[12:13]
	v_cvt_f32_u32_e32 v4, v2
	s_waitcnt vmcnt(0)
	v_readfirstlane_b32 s10, v3
	v_sub_u32_e32 v3, 0, v2
	v_rcp_iflag_f32_e32 v4, v4
	v_add_u32_e32 v5, s10, v1
	v_mul_f32_e32 v4, 0x4f7ffffe, v4
	v_cvt_u32_f32_e32 v4, v4
	v_mul_lo_u32 v1, v3, v4
	v_mul_hi_u32 v1, v4, v1
	v_add_u32_e32 v1, v4, v1
	v_mul_hi_u32 v1, v5, v1
	v_mul_lo_u32 v3, v1, v2
	v_sub_u32_e32 v3, v5, v3
	v_add_u32_e32 v4, 1, v1
	v_cmp_ge_u32_e32 vcc, v3, v2
	s_nop 1
	v_cndmask_b32_e32 v1, v1, v4, vcc
	v_sub_u32_e32 v4, v3, v2
	v_cndmask_b32_e32 v3, v3, v4, vcc
	v_add_u32_e32 v4, 1, v1
	v_cmp_ge_u32_e32 vcc, v3, v2
	v_add_u32_e32 v3, 1, v5
	s_nop 0
	v_cndmask_b32_e32 v1, v1, v4, vcc
	v_mul_lo_u32 v4, v2, v1
	v_add_u32_e32 v2, v4, v2
	v_cmp_ne_u32_e32 vcc, v3, v2
	s_and_saveexec_b64 s[10:11], vcc
	s_xor_b64 s[10:11], exec, s[10:11]
	s_cbranch_execz .LBB0_1007
	s_waitcnt lgkmcnt(0)
	v_mov_b32_e32 v0, 0x21824
	ds_read_b32 v0, v0
	s_waitcnt lgkmcnt(0)
	v_mad_u32_u24 v1, v1, v0, v0
	v_mov_b32_e32 v0, 0x3000
	global_load_dword v0, v0, s[40:41] offset:1024 sc1
	s_add_u32 s16, s40, 0x3400
	s_addc_u32 s17, s41, 0
	s_waitcnt vmcnt(0)
	v_cmp_lt_u32_e32 vcc, v0, v1
	s_and_saveexec_b64 s[12:13], vcc
	s_cbranch_execz .LBB0_1006
	s_add_u32 s14, s38, 0x1b000200
	s_addc_u32 s15, s39, 0
	s_mov_b32 s30, 1
	s_mov_b64 s[18:19], 0
	v_mov_b32_e32 v0, 0
	s_branch .LBB0_997

.LBB0_1001:
	global_load_dword v2, v0, s[16:17] sc1
	s_add_i32 s30, s30, 1
	s_mov_b64 s[24:25], -1
	s_waitcnt vmcnt(0)
	v_cmp_ge_u32_e32 vcc, v2, v1
	s_orn2_b64 s[22:23], vcc, exec
	s_branch .LBB0_996

.LBB0_1010:
	s_or_b64 exec, exec, s[12:13]
	v_cvt_f32_u32_e32 v3, v0
	s_waitcnt vmcnt(0)
	v_readfirstlane_b32 s10, v2
	s_add_u32 s12, s38, 0x1b003400
	s_addc_u32 s13, s39, 0
	v_rcp_iflag_f32_e32 v3, v3
	v_add_u32_e32 v1, s10, v1
	v_add_u32_e32 v4, 1, v1
	s_mov_b64 s[14:15], 0
	v_mul_f32_e32 v2, 0x4f7ffffe, v3
	v_cvt_u32_f32_e32 v2, v2
	v_sub_u32_e32 v3, 0, v0
	v_mul_lo_u32 v3, v3, v2
	v_mul_hi_u32 v3, v2, v3
	v_add_u32_e32 v2, v2, v3
	v_mul_hi_u32 v2, v1, v2
	v_mul_lo_u32 v3, v2, v0
	v_sub_u32_e32 v1, v1, v3
	v_add_u32_e32 v5, 1, v2
	v_cmp_ge_u32_e32 vcc, v1, v0
	v_sub_u32_e32 v3, v1, v0
	s_nop 0
	v_cndmask_b32_e32 v2, v2, v5, vcc
	v_cndmask_b32_e32 v1, v1, v3, vcc
	v_add_u32_e32 v3, 1, v2
	v_cmp_ge_u32_e32 vcc, v1, v0
	s_nop 1
	v_cndmask_b32_e32 v2, v2, v3, vcc
	v_mul_lo_u32 v1, v0, v2
	v_add_u32_e32 v0, v1, v0
	v_cmp_ne_u32_e32 vcc, v4, v0
	v_mov_b32_e32 v2, v0
	v_mov_b64_e32 v[0:1], s[12:13]
	s_and_saveexec_b64 s[10:11], vcc
	s_cbranch_execz .LBB0_1022
	v_mov_b32_e32 v0, 0
	global_load_dword v1, v0, s[12:13] sc1
	s_mov_b64 s[18:19], 0
	s_waitcnt vmcnt(0)
	v_cmp_lt_u32_e32 vcc, v1, v2
	s_and_saveexec_b64 s[16:17], vcc
	s_cbranch_execz .LBB0_1021
	s_add_u32 s14, s38, 0x1b000200
	s_addc_u32 s15, s39, 0
	s_mov_b32 s30, 1
	s_branch .LBB0_1014

.LBB0_1018:
	global_load_dword v1, v0, s[12:13] sc1
	s_add_i32 s30, s30, 1
	s_mov_b64 s[22:23], -1
	s_waitcnt vmcnt(0)
	v_cmp_ge_u32_e32 vcc, v1, v2
	s_orn2_b64 s[26:27], vcc, exec
	s_branch .LBB0_1013

.LBB0_1268:
	s_or_b64 exec, exec, s[10:11]
	v_cvt_f32_u32_e32 v20, v18
	s_waitcnt vmcnt(0)
	v_readfirstlane_b32 s4, v19
	v_sub_u32_e32 v19, 0, v18
	v_rcp_iflag_f32_e32 v20, v20
	v_add_u32_e32 v21, s4, v17
	v_mul_f32_e32 v20, 0x4f7ffffe, v20
	v_cvt_u32_f32_e32 v20, v20
	v_mul_lo_u32 v17, v19, v20
	v_mul_hi_u32 v17, v20, v17
	v_add_u32_e32 v17, v20, v17
	v_mul_hi_u32 v17, v21, v17
	v_mul_lo_u32 v19, v17, v18
	v_sub_u32_e32 v19, v21, v19
	v_add_u32_e32 v20, 1, v17
	v_cmp_ge_u32_e32 vcc, v19, v18
	s_nop 1
	v_cndmask_b32_e32 v17, v17, v20, vcc
	v_sub_u32_e32 v20, v19, v18
	v_cndmask_b32_e32 v19, v19, v20, vcc
	v_add_u32_e32 v20, 1, v17
	v_cmp_ge_u32_e32 vcc, v19, v18
	v_add_u32_e32 v19, 1, v21
	s_nop 0
	v_cndmask_b32_e32 v17, v17, v20, vcc
	v_mul_lo_u32 v20, v18, v17
	v_add_u32_e32 v18, v20, v18
	v_cmp_ne_u32_e32 vcc, v19, v18
	s_and_saveexec_b64 s[4:5], vcc
	s_xor_b64 s[4:5], exec, s[4:5]
	s_cbranch_execz .LBB0_1282
	s_waitcnt lgkmcnt(0)
	v_mov_b32_e32 v16, 0x21824
	ds_read_b32 v16, v16
	s_waitcnt lgkmcnt(0)
	v_mad_u32_u24 v17, v17, v16, v16
	v_mov_b32_e32 v16, 0x3000
	global_load_dword v16, v16, s[40:41] offset:1024 sc1
	s_add_u32 s14, s40, 0x3400
	s_addc_u32 s15, s41, 0
	s_waitcnt vmcnt(0)
	v_cmp_lt_u32_e32 vcc, v16, v17
	s_and_saveexec_b64 s[10:11], vcc
	s_cbranch_execz .LBB0_1281
	s_add_u32 s12, s38, 0x1b000200
	s_addc_u32 s13, s39, 0
	s_mov_b32 s26, 1
	s_mov_b64 s[16:17], 0
	v_mov_b32_e32 v16, 0
	s_branch .LBB0_1272

.LBB0_1276:
	global_load_dword v18, v16, s[14:15] sc1
	s_add_i32 s26, s26, 1
	s_mov_b64 s[22:23], -1
	s_waitcnt vmcnt(0)
	v_cmp_ge_u32_e32 vcc, v18, v17
	s_orn2_b64 s[20:21], vcc, exec
	s_branch .LBB0_1271

.LBB0_1285:
	s_or_b64 exec, exec, s[10:11]
	v_cvt_f32_u32_e32 v19, v16
	s_waitcnt vmcnt(0)
	v_readfirstlane_b32 s4, v18
	s_add_u32 s10, s38, 0x1b003400
	s_addc_u32 s11, s39, 0
	v_rcp_iflag_f32_e32 v19, v19
	v_add_u32_e32 v17, s4, v17
	v_add_u32_e32 v20, 1, v17
	s_mov_b64 s[12:13], 0
	v_mul_f32_e32 v18, 0x4f7ffffe, v19
	v_cvt_u32_f32_e32 v18, v18
	v_sub_u32_e32 v19, 0, v16
	v_mul_lo_u32 v19, v19, v18
	v_mul_hi_u32 v19, v18, v19
	v_add_u32_e32 v18, v18, v19
	v_mul_hi_u32 v18, v17, v18
	v_mul_lo_u32 v19, v18, v16
	v_sub_u32_e32 v17, v17, v19
	v_add_u32_e32 v21, 1, v18
	v_cmp_ge_u32_e32 vcc, v17, v16
	v_sub_u32_e32 v19, v17, v16
	s_nop 0
	v_cndmask_b32_e32 v18, v18, v21, vcc
	v_cndmask_b32_e32 v17, v17, v19, vcc
	v_add_u32_e32 v19, 1, v18
	v_cmp_ge_u32_e32 vcc, v17, v16
	s_nop 1
	v_cndmask_b32_e32 v18, v18, v19, vcc
	v_mul_lo_u32 v17, v16, v18
	v_add_u32_e32 v16, v17, v16
	v_cmp_ne_u32_e32 vcc, v20, v16
	v_mov_b32_e32 v18, v16
	v_mov_b64_e32 v[16:17], s[10:11]
	s_and_saveexec_b64 s[4:5], vcc
	s_cbranch_execz .LBB0_1297
	v_mov_b32_e32 v16, 0
	global_load_dword v17, v16, s[10:11] sc1
	s_mov_b64 s[16:17], 0
	s_waitcnt vmcnt(0)
	v_cmp_lt_u32_e32 vcc, v17, v18
	s_and_saveexec_b64 s[14:15], vcc
	s_cbranch_execz .LBB0_1296
	s_add_u32 s12, s38, 0x1b000200
	s_addc_u32 s13, s39, 0
	s_mov_b32 s26, 1
	s_branch .LBB0_1289

.LBB0_1293:
	global_load_dword v17, v16, s[10:11] sc1
	s_add_i32 s26, s26, 1
	s_mov_b64 s[20:21], -1
	s_waitcnt vmcnt(0)
	v_cmp_ge_u32_e32 vcc, v17, v18
	s_orn2_b64 s[24:25], vcc, exec
	s_branch .LBB0_1288
